# MLA K/V staging by LDS-DMA (global_load_lds_dwordx4, per-lane gather into the padded LDS image) instead of global_load + ds_write
# speedup vs baseline: 1.0082x; 1.0036x over previous
.LBB0_789:
	s_waitcnt lgkmcnt(0)
	v_pk_add_f32 v[80:81], v[80:81], v[82:83]
	v_mul_lo_u32 v199, v222, s45
	v_pk_fma_f32 v[196:197], v[80:81], s[28:29], v[158:159] op_sel_hi:[1,1,0]
	v_lshlrev_b32_e32 v84, 4, v223
	v_mul_f32_e32 v80, 0x4b800000, v197
	v_cmp_gt_f32_e32 vcc, s46, v197
	v_lshlrev_b32_e32 v85, 4, v219
	v_and_b32_e32 v194, 0x70, v85
	v_cndmask_b32_e32 v80, v197, v80, vcc
	v_rsq_f32_e32 v80, v80
	v_mad_u64_u32 v[168:169], s[0:1], v222, s44, v[84:85]
	v_mad_u64_u32 v[170:171], s[0:1], v221, s44, v[84:85]
	v_mul_f32_e32 v81, 0x45800000, v80
	v_cndmask_b32_e32 v80, v80, v81, vcc
	v_mul_f32_e32 v198, 0x3dd53b94, v80
	v_pk_mul_f32 v[108:109], v[198:199], v[108:109] op_sel_hi:[0,1]
	v_pk_mul_f32 v[118:119], v[198:199], v[118:119] op_sel_hi:[0,1]
	v_cvt_pk_bf16_f32 v108, v108, v109
	v_cvt_pk_bf16_f32 v109, v118, v119
	v_mul_f32_e32 v118, 0x4b800000, v196
	v_cmp_gt_f32_e32 vcc, s46, v196
	v_pk_mul_f32 v[80:81], v[198:199], v[190:191] op_sel_hi:[0,1]
	v_pk_mul_f32 v[82:83], v[198:199], v[186:187] op_sel_hi:[0,1]
	v_cndmask_b32_e32 v118, v196, v118, vcc
	v_rsq_f32_e32 v118, v118
	v_cvt_pk_bf16_f32 v80, v80, v81
	v_cvt_pk_bf16_f32 v81, v82, v83
	v_pk_mul_f32 v[82:83], v[198:199], v[184:185] op_sel_hi:[0,1]
	v_pk_mul_f32 v[84:85], v[198:199], v[182:183] op_sel_hi:[0,1]
	v_cvt_pk_bf16_f32 v82, v82, v83
	v_cvt_pk_bf16_f32 v83, v84, v85
	v_pk_mul_f32 v[84:85], v[198:199], v[180:181] op_sel_hi:[0,1]
	v_pk_mul_f32 v[86:87], v[198:199], v[176:177] op_sel_hi:[0,1]
	v_pk_mul_f32 v[110:111], v[198:199], v[110:111] op_sel_hi:[0,1]
	v_pk_mul_f32 v[116:117], v[198:199], v[116:117] op_sel_hi:[0,1]
	v_cvt_pk_bf16_f32 v84, v84, v85
	v_cvt_pk_bf16_f32 v85, v86, v87
	v_pk_mul_f32 v[86:87], v[198:199], v[172:173] op_sel_hi:[0,1]
	v_pk_mul_f32 v[154:155], v[198:199], v[154:155] op_sel_hi:[0,1]
	v_cvt_pk_bf16_f32 v110, v110, v111
	v_cvt_pk_bf16_f32 v111, v116, v117
	v_mul_f32_e32 v116, 0x45800000, v118
	v_cvt_pk_bf16_f32 v86, v86, v87
	v_cvt_pk_bf16_f32 v87, v154, v155
	v_cndmask_b32_e32 v154, v118, v116, vcc
	v_pk_mul_f32 v[116:117], v[154:155], v[208:209] op_sel_hi:[0,1]
	s_waitcnt vmcnt(10)
	v_pk_mul_f32 v[68:69], v[68:69], v[116:117]
	v_pk_mul_f32 v[116:117], v[154:155], v[210:211] op_sel_hi:[0,1]
	s_waitcnt vmcnt(8)
	v_pk_mul_f32 v[76:77], v[76:77], v[116:117]
	s_lshl_b32 s52, s12, 2
	s_waitcnt vmcnt(0)
	v_pk_mul_f32 v[116:117], v[112:113], v[76:77]
	s_add_i32 s52, s52, 4
	v_pk_fma_f32 v[116:117], v[72:73], v[68:69], v[116:117] neg_lo:[0,0,1] neg_hi:[0,0,1]
	v_pk_mul_f32 v[72:73], v[72:73], v[76:77]
	s_add_u32 s0, s40, 0x60000
	v_pk_fma_f32 v[68:69], v[112:113], v[68:69], v[72:73]
	v_pk_mul_f32 v[72:73], v[154:155], v[204:205] op_sel_hi:[0,1]
	v_pk_mul_f32 v[70:71], v[70:71], v[72:73]
	v_pk_mul_f32 v[72:73], v[154:155], v[206:207] op_sel_hi:[0,1]
	v_pk_mul_f32 v[72:73], v[78:79], v[72:73]
	s_addc_u32 s1, s41, 0
	v_pk_mul_f32 v[76:77], v[114:115], v[72:73]
	v_pk_mul_f32 v[72:73], v[74:75], v[72:73]
	v_pk_fma_f32 v[76:77], v[74:75], v[70:71], v[76:77] neg_lo:[0,0,1] neg_hi:[0,0,1]
	v_pk_fma_f32 v[70:71], v[114:115], v[70:71], v[72:73]
	v_pk_mul_f32 v[72:73], v[154:155], v[200:201] op_sel_hi:[0,1]
	v_pk_mul_f32 v[52:53], v[52:53], v[72:73]
	v_pk_mul_f32 v[72:73], v[154:155], v[202:203] op_sel_hi:[0,1]
	v_pk_mul_f32 v[56:57], v[56:57], v[72:73]
	v_pk_mul_f32 v[100:101], v[198:199], v[100:101] op_sel_hi:[0,1]
	v_pk_mul_f32 v[72:73], v[64:65], v[56:57]
	v_pk_mul_f32 v[56:57], v[60:61], v[56:57]
	v_pk_fma_f32 v[72:73], v[60:61], v[52:53], v[72:73] neg_lo:[0,0,1] neg_hi:[0,0,1]
	v_pk_fma_f32 v[52:53], v[64:65], v[52:53], v[56:57]
	v_pk_mul_f32 v[126:127], v[198:199], v[126:127] op_sel_hi:[0,1]
	v_pk_mul_f32 v[52:53], v[52:53], s[36:37] op_sel_hi:[1,0]
	v_pk_mul_f32 v[102:103], v[198:199], v[102:103] op_sel_hi:[0,1]
	v_cvt_pk_bf16_f32 v118, v52, v53
	v_pk_mul_f32 v[52:53], v[154:155], v[174:175] op_sel_hi:[0,1]
	v_pk_mul_f32 v[40:41], v[40:41], v[52:53]
	v_pk_mul_f32 v[52:53], v[154:155], v[178:179] op_sel_hi:[0,1]
	v_pk_mul_f32 v[36:37], v[52:53], v[36:37]
	v_pk_mul_f32 v[124:125], v[198:199], v[124:125] op_sel_hi:[0,1]
	v_pk_mul_f32 v[52:53], v[36:37], v[48:49]
	v_pk_mul_f32 v[104:105], v[198:199], v[104:105] op_sel_hi:[0,1]
	v_pk_fma_f32 v[52:53], v[40:41], v[44:45], v[52:53] neg_lo:[0,0,1] neg_hi:[0,0,1]
	v_pk_mul_f32 v[40:41], v[40:41], v[48:49]
	v_pk_mul_f32 v[122:123], v[198:199], v[122:123] op_sel_hi:[0,1]
	v_pk_fma_f32 v[36:37], v[44:45], v[36:37], v[40:41]
	v_pk_mul_f32 v[40:41], v[154:155], v[150:151] op_sel_hi:[0,1]
	v_pk_mul_f32 v[40:41], v[40:41], v[42:43]
	v_pk_mul_f32 v[42:43], v[154:155], v[152:153] op_sel_hi:[0,1]
	v_pk_mul_f32 v[38:39], v[42:43], v[38:39]
	v_pk_mul_f32 v[106:107], v[198:199], v[106:107] op_sel_hi:[0,1]
	v_pk_mul_f32 v[42:43], v[38:39], v[50:51]
	v_pk_mul_f32 v[120:121], v[198:199], v[120:121] op_sel_hi:[0,1]
	v_pk_fma_f32 v[42:43], v[40:41], v[46:47], v[42:43] neg_lo:[0,0,1] neg_hi:[0,0,1]
	v_pk_mul_f32 v[40:41], v[40:41], v[50:51]
	v_cvt_pk_bf16_f32 v100, v100, v101
	v_pk_fma_f32 v[38:39], v[46:47], v[38:39], v[40:41]
	v_lshlrev_b64 v[40:41], 1, v[162:163]
	v_lshlrev_b64 v[46:47], 1, v[164:165]
	v_lshl_add_u64 v[44:45], s[0:1], 0, v[40:41]
	v_lshl_add_u64 v[48:49], s[0:1], 0, v[46:47]
	s_add_u32 s0, s40, 0x60100
	v_cvt_pk_bf16_f32 v101, v126, v127
	v_cvt_pk_bf16_f32 v102, v102, v103
	v_cvt_pk_bf16_f32 v103, v124, v125
	v_cvt_pk_bf16_f32 v104, v104, v105
	v_cvt_pk_bf16_f32 v105, v122, v123
	v_cvt_pk_bf16_f32 v106, v106, v107
	v_cvt_pk_bf16_f32 v107, v120, v121
	v_add_co_u32_e32 v44, vcc, s47, v166
	s_addc_u32 s1, s41, 0
	v_pk_mul_f32 v[92:93], v[198:199], v[92:93] op_sel_hi:[0,1]
	v_pk_mul_f32 v[134:135], v[198:199], v[134:135] op_sel_hi:[0,1]
	v_pk_mul_f32 v[94:95], v[198:199], v[94:95] op_sel_hi:[0,1]
	v_pk_mul_f32 v[132:133], v[198:199], v[132:133] op_sel_hi:[0,1]
	v_pk_mul_f32 v[96:97], v[198:199], v[96:97] op_sel_hi:[0,1]
	v_pk_mul_f32 v[130:131], v[198:199], v[130:131] op_sel_hi:[0,1]
	v_pk_mul_f32 v[98:99], v[198:199], v[98:99] op_sel_hi:[0,1]
	v_pk_mul_f32 v[128:129], v[198:199], v[128:129] op_sel_hi:[0,1]
	v_addc_co_u32_e32 v45, vcc, 0, v167, vcc
	v_lshl_add_u64 v[40:41], s[0:1], 0, v[40:41]
	v_pk_mul_f32 v[88:89], v[198:199], v[88:89] op_sel_hi:[0,1]
	v_pk_mul_f32 v[138:139], v[198:199], v[138:139] op_sel_hi:[0,1]
	v_pk_mul_f32 v[90:91], v[198:199], v[90:91] op_sel_hi:[0,1]
	v_pk_mul_f32 v[136:137], v[198:199], v[136:137] op_sel_hi:[0,1]
	v_cvt_pk_bf16_f32 v92, v92, v93
	v_cvt_pk_bf16_f32 v93, v134, v135
	v_cvt_pk_bf16_f32 v94, v94, v95
	v_cvt_pk_bf16_f32 v95, v132, v133
	v_cvt_pk_bf16_f32 v96, v96, v97
	v_cvt_pk_bf16_f32 v97, v130, v131
	v_cvt_pk_bf16_f32 v98, v98, v99
	v_cvt_pk_bf16_f32 v99, v128, v129
	v_lshl_add_u64 v[40:41], s[0:1], 0, v[46:47]
	v_cvt_pk_bf16_f32 v88, v88, v89
	v_cvt_pk_bf16_f32 v89, v138, v139
	v_cvt_pk_bf16_f32 v90, v90, v91
	v_cvt_pk_bf16_f32 v91, v136, v137
	s_mov_b32 s98, 0x0a3d70a4
	s_mov_b32 s99, 0x0ccccccd
	s_movk_i32 s100, 0x1800
	v_and_b32_e32 v240, 63, v212
	v_lshlrev_b32_e32 v241, 4, v212
	s_lshl_b32 s101, s13, 6
	v_add_u32_e32 v242, s101, v240
	v_mul_hi_u32 v243, v242, s98
	v_mul_u32_u24_e32 v244, 25, v243
	v_sub_u32_e32 v244, v242, v244
	v_cmp_gt_u32_e32 vcc, 16, v244
	v_lshlrev_b32_e32 v245, 4, v244
	v_lshlrev_b32_e32 v246, 7, v243
	v_cndmask_b32_e32 v245, 0, v245, vcc
	v_mad_u32_u24 v245, v243, s100, v245
	v_lshl_add_u32 v246, v244, 4, v246
	v_sub_u32_e32 v246, v246, v241
	v_add_u32_e32 v246, 0xffffff00, v246
	v_add_u32_e32 v247, -16, v244
	v_cmp_gt_u32_e32 vcc, 8, v247
	v_mov_b32_e32 v248, v245
	v_mov_b32_e32 v249, 0
	v_lshl_add_u64 v[248:249], v[248:249], 0, s[40:41]
	v_ashrrev_i32_e32 v251, 31, v246
	v_mov_b32_e32 v250, v246
	v_lshl_add_u64 v[250:251], v[250:251], 0, v[166:167]
	v_cndmask_b32_e32 v120, v248, v250, vcc
	v_cndmask_b32_e32 v121, v249, v251, vcc
	v_mov_b32_e32 v247, 0x2000
	v_mov_b32_e32 v132, 0x60000
	v_cndmask_b32_e32 v132, v132, v247, vcc
	s_lshl_b32 s101, s13, 6
	s_add_i32 s101, s101, 512
	v_add_u32_e32 v242, s101, v240
	v_mul_hi_u32 v243, v242, s98
	v_mul_u32_u24_e32 v244, 25, v243
	v_sub_u32_e32 v244, v242, v244
	v_cmp_gt_u32_e32 vcc, 16, v244
	v_lshlrev_b32_e32 v245, 4, v244
	v_lshlrev_b32_e32 v246, 7, v243
	v_cndmask_b32_e32 v245, 0, v245, vcc
	v_mad_u32_u24 v245, v243, s100, v245
	v_lshl_add_u32 v246, v244, 4, v246
	v_sub_u32_e32 v246, v246, v241
	v_add_u32_e32 v246, 0xffffff00, v246
	v_add_u32_e32 v247, -16, v244
	v_cmp_gt_u32_e32 vcc, 8, v247
	v_mov_b32_e32 v248, v245
	v_mov_b32_e32 v249, 0
	v_lshl_add_u64 v[248:249], v[248:249], 0, s[40:41]
	v_ashrrev_i32_e32 v251, 31, v246
	v_mov_b32_e32 v250, v246
	v_lshl_add_u64 v[250:251], v[250:251], 0, v[166:167]
	v_cndmask_b32_e32 v122, v248, v250, vcc
	v_cndmask_b32_e32 v123, v249, v251, vcc
	v_mov_b32_e32 v247, 0x2000
	v_mov_b32_e32 v133, 0x60000
	v_cndmask_b32_e32 v133, v133, v247, vcc
	s_lshl_b32 s101, s13, 6
	s_add_i32 s101, s101, 1024
	v_add_u32_e32 v242, s101, v240
	v_mul_hi_u32 v243, v242, s98
	v_mul_u32_u24_e32 v244, 25, v243
	v_sub_u32_e32 v244, v242, v244
	v_cmp_gt_u32_e32 vcc, 16, v244
	v_lshlrev_b32_e32 v245, 4, v244
	v_lshlrev_b32_e32 v246, 7, v243
	v_cndmask_b32_e32 v245, 0, v245, vcc
	v_mad_u32_u24 v245, v243, s100, v245
	v_lshl_add_u32 v246, v244, 4, v246
	v_sub_u32_e32 v246, v246, v241
	v_add_u32_e32 v246, 0xffffff00, v246
	v_add_u32_e32 v247, -16, v244
	v_cmp_gt_u32_e32 vcc, 8, v247
	v_mov_b32_e32 v248, v245
	v_mov_b32_e32 v249, 0
	v_lshl_add_u64 v[248:249], v[248:249], 0, s[40:41]
	v_ashrrev_i32_e32 v251, 31, v246
	v_mov_b32_e32 v250, v246
	v_lshl_add_u64 v[250:251], v[250:251], 0, v[166:167]
	v_cndmask_b32_e32 v124, v248, v250, vcc
	v_cndmask_b32_e32 v125, v249, v251, vcc
	v_mov_b32_e32 v247, 0x2000
	v_mov_b32_e32 v134, 0x60000
	v_cndmask_b32_e32 v134, v134, v247, vcc
	s_lshl_b32 s101, s13, 6
	s_add_i32 s101, s101, 1536
	v_add_u32_e32 v242, s101, v240
	s_cmp_eq_u32 s13, 0
	s_cbranch_scc0 .Ldma_j3v
	v_mul_hi_u32 v243, v242, s98
	v_mul_u32_u24_e32 v244, 25, v243
	v_sub_u32_e32 v244, v242, v244
	v_cmp_gt_u32_e32 vcc, 16, v244
	v_lshlrev_b32_e32 v245, 4, v244
	v_lshlrev_b32_e32 v246, 7, v243
	v_cndmask_b32_e32 v245, 0, v245, vcc
	v_mad_u32_u24 v245, v243, s100, v245
	v_lshl_add_u32 v246, v244, 4, v246
	v_sub_u32_e32 v246, v246, v241
	v_add_u32_e32 v246, 0xffffff00, v246
	v_add_u32_e32 v247, -16, v244
	v_cmp_gt_u32_e32 vcc, 8, v247
	v_mov_b32_e32 v248, v245
	v_mov_b32_e32 v249, 0
	v_lshl_add_u64 v[248:249], v[248:249], 0, s[40:41]
	v_ashrrev_i32_e32 v251, 31, v246
	v_mov_b32_e32 v250, v246
	v_lshl_add_u64 v[250:251], v[250:251], 0, v[166:167]
	v_cndmask_b32_e32 v126, v248, v250, vcc
	v_cndmask_b32_e32 v127, v249, v251, vcc
	v_mov_b32_e32 v247, 0x2000
	v_mov_b32_e32 v135, 0x60000
	v_cndmask_b32_e32 v135, v135, v247, vcc
	s_branch .Ldma_j3d
.Ldma_j3v:
	v_add_u32_e32 v242, 0xfffff9c0, v242
	v_mul_hi_u32 v243, v242, s99
	v_mul_u32_u24_e32 v244, 20, v243
	v_sub_u32_e32 v244, v242, v244
	v_cmp_gt_u32_e32 vcc, 16, v244
	v_lshlrev_b32_e32 v245, 4, v244
	v_mov_b32_e32 v249, 0
	v_cndmask_b32_e32 v245, 0, v245, vcc
	v_mad_u32_u24 v245, v243, s100, v245
	v_add_u32_e32 v248, 0x100, v245
	v_lshl_add_u64 v[126:127], v[248:249], 0, s[40:41]
	v_mov_b32_e32 v135, 0x60000
.Ldma_j3d:
	s_lshl_b32 s101, s13, 6
	s_add_i32 s101, s101, 2048
	v_add_u32_e32 v242, s101, v240
	v_add_u32_e32 v242, 0xfffff9c0, v242
	v_mul_hi_u32 v243, v242, s99
	v_mul_u32_u24_e32 v244, 20, v243
	v_sub_u32_e32 v244, v242, v244
	v_cmp_gt_u32_e32 vcc, 16, v244
	v_lshlrev_b32_e32 v245, 4, v244
	v_mov_b32_e32 v249, 0
	v_cndmask_b32_e32 v245, 0, v245, vcc
	v_mad_u32_u24 v245, v243, s100, v245
	v_add_u32_e32 v248, 0x100, v245
	v_lshl_add_u64 v[128:129], v[248:249], 0, s[40:41]
	v_mov_b32_e32 v136, 0x60000
	s_lshl_b32 s101, s13, 6
	s_add_i32 s101, s101, 2560
	v_add_u32_e32 v242, s101, v240
	v_add_u32_e32 v242, 0xfffff9c0, v242
	v_mul_hi_u32 v243, v242, s99
	v_mul_u32_u24_e32 v244, 20, v243
	v_sub_u32_e32 v244, v242, v244
	v_cmp_gt_u32_e32 vcc, 16, v244
	v_lshlrev_b32_e32 v245, 4, v244
	v_mov_b32_e32 v249, 0
	v_cndmask_b32_e32 v245, 0, v245, vcc
	v_mad_u32_u24 v245, v243, s100, v245
	v_add_u32_e32 v248, 0x100, v245
	v_lshl_add_u64 v[130:131], v[248:249], 0, s[40:41]
	v_mov_b32_e32 v137, 0x60000
	v_pk_mul_f32 v[40:41], v[154:155], v[144:145] op_sel_hi:[0,1]
	v_pk_mul_f32 v[16:17], v[40:41], v[16:17]
	v_pk_mul_f32 v[40:41], v[154:155], v[146:147] op_sel_hi:[0,1]
	v_pk_mul_f32 v[20:21], v[40:41], v[20:21]
	v_lshlrev_b32_e32 v195, 3, v218
	v_pk_mul_f32 v[40:41], v[20:21], v[24:25]
	v_lshrrev_b32_e32 v149, 3, v219
	v_pk_fma_f32 v[40:41], v[16:17], v[32:33], v[40:41] neg_lo:[0,0,1] neg_hi:[0,0,1]
	v_pk_mul_f32 v[16:17], v[16:17], v[24:25]
	v_mad_u64_u32 v[172:173], s[0:1], v149, s44, v[194:195]
	v_pk_fma_f32 v[16:17], v[32:33], v[20:21], v[16:17]
	v_pk_mul_f32 v[20:21], v[154:155], v[140:141] op_sel_hi:[0,1]
	v_pk_mul_f32 v[16:17], v[16:17], s[36:37] op_sel_hi:[1,0]
	v_pk_mul_f32 v[56:57], v[154:155], v[188:189] op_sel_hi:[0,1]
	v_cvt_pk_bf16_f32 v146, v16, v17
	v_add_u32_e32 v16, 0, v168
	ds_write_b128 v16, v[12:15]
	v_add_u32_e32 v12, 0, v170
	v_pk_mul_f32 v[18:19], v[20:21], v[18:19]
	v_pk_mul_f32 v[20:21], v[154:155], v[142:143] op_sel_hi:[0,1]
	ds_write_b128 v12, v[4:7]
	v_add_u32_e32 v4, 0, v172
	v_mul_lo_u32 v197, v221, s45
	v_pk_mul_f32 v[54:55], v[54:55], v[56:57]
	v_pk_mul_f32 v[56:57], v[154:155], v[192:193] op_sel_hi:[0,1]
	v_pk_mul_f32 v[20:21], v[20:21], v[22:23]
	ds_write_b128 v4, v[8:11] offset:256
	v_add_u32_e32 v4, v16, v199
	v_pk_mul_f32 v[56:57], v[58:59], v[56:57]
	v_pk_mul_f32 v[22:23], v[20:21], v[26:27]
	ds_write_b128 v4, v[0:3] offset:25600
	v_add_u32_e32 v0, v12, v197
	v_pk_mul_f32 v[58:59], v[66:67], v[56:57]
	v_pk_mul_f32 v[56:57], v[62:63], v[56:57]
	v_pk_fma_f32 v[22:23], v[18:19], v[34:35], v[22:23] neg_lo:[0,0,1] neg_hi:[0,0,1]
	v_pk_mul_f32 v[18:19], v[18:19], v[26:27]
	ds_write_b128 v0, v[28:31] offset:25600
	v_lshlrev_b32_e32 v175, 2, v218
	v_lshrrev_b32_e32 v0, 2, v219
	v_pk_fma_f32 v[58:59], v[62:63], v[54:55], v[58:59] neg_lo:[0,0,1] neg_hi:[0,0,1]
	v_pk_fma_f32 v[54:55], v[66:67], v[54:55], v[56:57]
	v_pk_fma_f32 v[18:19], v[34:35], v[20:21], v[18:19]
	v_and_or_b32 v0, v0, 3, v175
	v_pk_mul_f32 v[58:59], v[58:59], s[36:37] op_sel_hi:[1,0]
	v_pk_mul_f32 v[54:55], v[54:55], s[36:37] op_sel_hi:[1,0]
	v_pk_mul_f32 v[52:53], v[52:53], s[36:37] op_sel_hi:[1,0]
	v_pk_mul_f32 v[36:37], v[36:37], s[36:37] op_sel_hi:[1,0]
	v_pk_mul_f32 v[42:43], v[42:43], s[36:37] op_sel_hi:[1,0]
	v_pk_mul_f32 v[38:39], v[38:39], s[36:37] op_sel_hi:[1,0]
	v_pk_mul_f32 v[40:41], v[40:41], s[36:37] op_sel_hi:[1,0]
	v_pk_mul_f32 v[22:23], v[22:23], s[36:37] op_sel_hi:[1,0]
	v_pk_mul_f32 v[18:19], v[18:19], s[36:37] op_sel_hi:[1,0]
	v_mul_u32_u24_e32 v176, 0x140, v0
	v_lshlrev_b32_e32 v0, 1, v219
	v_mov_b32_e32 v14, v157
	v_mov_b32_e32 v15, v157
	v_pk_mul_f32 v[116:117], v[116:117], s[36:37] op_sel_hi:[1,0]
	v_pk_mul_f32 v[68:69], v[68:69], s[36:37] op_sel_hi:[1,0]
	v_pk_mul_f32 v[76:77], v[76:77], s[36:37] op_sel_hi:[1,0]
	v_pk_mul_f32 v[70:71], v[70:71], s[36:37] op_sel_hi:[1,0]
	v_pk_mul_f32 v[72:73], v[72:73], s[36:37] op_sel_hi:[1,0]
	v_cvt_pk_bf16_f32 v115, v58, v59
	v_cvt_pk_bf16_f32 v119, v54, v55
	v_cvt_pk_bf16_f32 v140, v52, v53
	v_cvt_pk_bf16_f32 v144, v36, v37
	v_cvt_pk_bf16_f32 v141, v42, v43
	v_cvt_pk_bf16_f32 v145, v38, v39
	v_cvt_pk_bf16_f32 v142, v40, v41
	v_cvt_pk_bf16_f32 v143, v22, v23
	v_cvt_pk_bf16_f32 v147, v18, v19
	v_and_b32_e32 v177, 32, v0
	v_mov_b32_e32 v0, v157
	v_mov_b32_e32 v1, v157
	v_mov_b32_e32 v2, v157
	v_mov_b32_e32 v3, v157
	v_mov_b32_e32 v4, v157
	v_mov_b32_e32 v5, v157
	v_mov_b32_e32 v6, v157
	v_mov_b32_e32 v7, v157
	v_mov_b32_e32 v8, v157
	v_mov_b32_e32 v9, v157
	v_mov_b32_e32 v10, v157
	v_mov_b32_e32 v11, v157
	v_mov_b32_e32 v12, v157
	v_mov_b32_e32 v13, v157
	v_mov_b64_e32 v[30:31], v[14:15]
	v_mov_b64_e32 v[46:47], v[14:15]
	v_mov_b64_e32 v[62:63], v[14:15]
	v_add_u32_e32 v169, v168, v199
	v_add_u32_e32 v171, v170, v197
	v_cvt_pk_bf16_f32 v112, v116, v117
	v_cvt_pk_bf16_f32 v116, v68, v69
	v_cvt_pk_bf16_f32 v113, v76, v77
	v_cvt_pk_bf16_f32 v117, v70, v71
	v_cvt_pk_bf16_f32 v114, v72, v73
	s_mov_b32 s53, 0
	v_mul_u32_u24_e32 v174, 0x190, v220
	v_and_b32_e32 v178, 24, v148
	s_or_b32 s54, s51, 31
	v_cmp_eq_u32_e64 s[0:1], 0, v218
	s_lshl_b32 s55, s26, 2
	v_mov_b32_e32 v180, 0xff800000
	v_mov_b32_e32 v173, 0
	s_movk_i32 s56, 0xff80
	v_mov_b64_e32 v[28:29], v[12:13]
	v_mov_b64_e32 v[26:27], v[10:11]
	v_mov_b64_e32 v[24:25], v[8:9]
	v_mov_b64_e32 v[22:23], v[6:7]
	v_mov_b64_e32 v[20:21], v[4:5]
	v_mov_b64_e32 v[18:19], v[2:3]
	v_mov_b64_e32 v[16:17], v[0:1]
	v_mov_b64_e32 v[44:45], v[12:13]
	v_mov_b64_e32 v[42:43], v[10:11]
	v_mov_b64_e32 v[40:41], v[8:9]
	v_mov_b64_e32 v[38:39], v[6:7]
	v_mov_b64_e32 v[36:37], v[4:5]
	v_mov_b64_e32 v[34:35], v[2:3]
	v_mov_b64_e32 v[32:33], v[0:1]
	v_mov_b64_e32 v[60:61], v[12:13]
	v_mov_b64_e32 v[58:59], v[10:11]
	v_mov_b64_e32 v[56:57], v[8:9]
	v_mov_b64_e32 v[54:55], v[6:7]
	v_mov_b64_e32 v[52:53], v[4:5]
	v_mov_b64_e32 v[50:51], v[2:3]
	v_mov_b64_e32 v[48:49], v[0:1]
	s_mov_b32 s57, 0
	s_waitcnt lgkmcnt(0)
	s_barrier
	s_branch .LBB0_792

.LBB0_791:
	s_add_i32 s26, s57, 1
	s_cmp_lg_u32 s26, 2
	s_cselect_b32 s57, s26, 0
	s_add_i32 s53, s53, 64
	s_add_i32 s56, s56, 1
	s_cmp_lg_u32 s55, s56
	s_waitcnt vmcnt(0) lgkmcnt(0)
	s_barrier
	s_cbranch_scc0 .LBB0_780
.LBB0_792:
	s_add_i32 s26, s56, 0x81
	s_cmp_ge_u32 s26, s52
	s_cbranch_scc1 .LBB0_796
	s_lshr_b32 s58, s53, 6
	s_add_i32 s58, s58, 1
	s_xor_b32 s26, s57, 1
	s_mul_i32 s26, s26, 0xb400
	s_lshl_b32 s59, s13, 10
	s_add_i32 s26, s26, s59
	v_mad_u64_u32 v[138:139], s[60:61], v132, s58, v[120:121]
	s_mov_b32 m0, s26
	s_nop 0
	global_load_lds_dwordx4 v[138:139], off
	v_mad_u64_u32 v[162:163], s[60:61], v133, s58, v[122:123]
	s_add_i32 m0, s26, 0x2000
	s_nop 0
	global_load_lds_dwordx4 v[162:163], off
	v_mad_u64_u32 v[138:139], s[60:61], v134, s58, v[124:125]
	s_add_i32 m0, s26, 0x4000
	s_nop 0
	global_load_lds_dwordx4 v[138:139], off
	v_mad_u64_u32 v[162:163], s[60:61], v135, s58, v[126:127]
	s_add_i32 m0, s26, 0x6000
	s_nop 0
	global_load_lds_dwordx4 v[162:163], off
	v_mad_u64_u32 v[138:139], s[60:61], v136, s58, v[128:129]
	s_add_i32 m0, s26, 0x8000
	s_nop 0
	global_load_lds_dwordx4 v[138:139], off
	s_cmp_gt_u32 s13, 4
	s_cbranch_scc1 .Ldma_skip5
	v_mad_u64_u32 v[162:163], s[60:61], v137, s58, v[130:131]
	s_add_i32 m0, s26, 0xa000
	s_nop 0
	global_load_lds_dwordx4 v[162:163], off
.Ldma_skip5:
.LBB0_796:
	s_mul_i32 s26, s57, 0xb400
	s_add_i32 s26, s26, 0
	v_add_u32_e32 v64, s26, v174
	v_add3_u32 v65, s26, v176, v177
	v_add_u32_e32 v181, v64, v156
	v_add_u32_e32 v179, v65, v178
	s_add_i32 s26, s53, 63
	s_cmp_le_i32 s26, s51
	s_cbranch_scc1 .Lmf_fast
	s_cmp_gt_i32 s53, s54
	s_cbranch_scc1 .LBB0_802
	ds_read_b128 v[64:67], v181
	ds_read_b128 v[148:151], v181 offset:32
	ds_read_b128 v[152:155], v181 offset:64
	s_add_i32 s26, s53, 31
	s_cmp_le_i32 s26, s51
	s_waitcnt lgkmcnt(2)
	v_mfma_f32_32x32x16_bf16 v[64:79], v[64:67], v[80:83], 0
	s_waitcnt lgkmcnt(1)
	v_mfma_f32_32x32x16_bf16 v[64:79], v[148:151], v[84:87], v[64:79]
	ds_read_b128 v[182:185], v181 offset:96
	s_waitcnt lgkmcnt(1)
	v_mfma_f32_32x32x16_bf16 v[64:79], v[152:155], v[88:91], v[64:79]
	ds_read_b128 v[148:151], v181 offset:128
	s_waitcnt lgkmcnt(1)
	v_mfma_f32_32x32x16_bf16 v[64:79], v[182:185], v[92:95], v[64:79]
	ds_read_b128 v[152:155], v181 offset:160
	s_waitcnt lgkmcnt(1)
	v_mfma_f32_32x32x16_bf16 v[64:79], v[148:151], v[96:99], v[64:79]
	ds_read_b128 v[182:185], v181 offset:192
	s_waitcnt lgkmcnt(1)
	v_mfma_f32_32x32x16_bf16 v[64:79], v[152:155], v[100:103], v[64:79]
	ds_read_b128 v[148:151], v181 offset:224
	s_waitcnt lgkmcnt(1)
	v_mfma_f32_32x32x16_bf16 v[64:79], v[182:185], v[104:107], v[64:79]
	ds_read_b128 v[152:155], v181 offset:256
	s_waitcnt lgkmcnt(1)
	v_mfma_f32_32x32x16_bf16 v[64:79], v[148:151], v[108:111], v[64:79]
	ds_read_b128 v[182:185], v181 offset:288
	s_waitcnt lgkmcnt(1)
	v_mfma_f32_32x32x16_bf16 v[64:79], v[152:155], v[112:115], v[64:79]
	ds_read_b128 v[148:151], v181 offset:320
	s_waitcnt lgkmcnt(1)
	v_mfma_f32_32x32x16_bf16 v[64:79], v[182:185], v[140:143], v[64:79]
	ds_read_b128 v[152:155], v181 offset:352
	s_waitcnt lgkmcnt(1)
	v_mfma_f32_32x32x16_bf16 v[64:79], v[148:151], v[116:119], v[64:79]
	s_waitcnt lgkmcnt(0)
	v_mfma_f32_32x32x16_bf16 v[64:79], v[152:155], v[144:147], v[64:79]
	ds_read_b64_tr_b16 v[152:153], v179 offset:25600
	ds_read_b64_tr_b16 v[154:155], v179 offset:28160
	ds_read_b64_tr_b16 v[150:151], v179 offset:28224
	ds_read_b64_tr_b16 v[148:149], v179 offset:25664
	s_cbranch_scc1 .LBB0_799
	v_add_u32_e32 v182, s53, v175
	v_cmp_lt_i32_e32 vcc, v182, v160
	v_add_u32_e32 v183, 2, v182
	s_nop 3
	v_cndmask_b32_e32 v65, v216, v65, vcc
	v_cmp_le_i32_e32 vcc, v182, v160
	s_nop 1
	v_cndmask_b32_e32 v64, v216, v64, vcc
	v_cmp_le_i32_e32 vcc, v183, v160
	v_add_u32_e32 v183, 3, v182
	s_nop 0
	v_cndmask_b32_e32 v66, v216, v66, vcc
	v_cmp_le_i32_e32 vcc, v183, v160
	v_add_u32_e32 v183, 8, v182
	s_nop 0
	v_cndmask_b32_e32 v67, v216, v67, vcc
	v_cmp_le_i32_e32 vcc, v183, v160
	v_add_u32_e32 v183, 9, v182
	s_nop 0
	v_cndmask_b32_e32 v68, v216, v68, vcc
	v_cmp_le_i32_e32 vcc, v183, v160
	v_add_u32_e32 v183, 10, v182
	s_nop 0
	v_cndmask_b32_e32 v69, v216, v69, vcc
	v_cmp_le_i32_e32 vcc, v183, v160
	v_add_u32_e32 v183, 11, v182
	s_nop 0
	v_cndmask_b32_e32 v70, v216, v70, vcc
	v_cmp_le_i32_e32 vcc, v183, v160
	v_add_u32_e32 v183, 16, v182
	s_nop 0
	v_cndmask_b32_e32 v71, v216, v71, vcc
	v_cmp_le_i32_e32 vcc, v183, v160
	v_add_u32_e32 v183, 17, v182
	s_nop 0
	v_cndmask_b32_e32 v72, v216, v72, vcc
	v_cmp_le_i32_e32 vcc, v183, v160
	v_add_u32_e32 v183, 18, v182
	s_nop 0
	v_cndmask_b32_e32 v73, v216, v73, vcc
	v_cmp_le_i32_e32 vcc, v183, v160
	v_add_u32_e32 v183, 19, v182
	s_nop 0
	v_cndmask_b32_e32 v74, v216, v74, vcc
	v_cmp_le_i32_e32 vcc, v183, v160
	v_add_u32_e32 v183, 24, v182
	s_nop 0
	v_cndmask_b32_e32 v75, v216, v75, vcc
	v_cmp_le_i32_e32 vcc, v183, v160
	v_add_u32_e32 v183, 25, v182
	s_nop 0
	v_cndmask_b32_e32 v76, v216, v76, vcc
	v_cmp_le_i32_e32 vcc, v183, v160
	v_add_u32_e32 v183, 26, v182
	v_add_u32_e32 v182, 27, v182
	v_cndmask_b32_e32 v77, v216, v77, vcc
	v_cmp_le_i32_e32 vcc, v183, v160
	s_nop 1
	v_cndmask_b32_e32 v78, v216, v78, vcc
	v_cmp_le_i32_e32 vcc, v182, v160
	s_nop 1
	v_cndmask_b32_e32 v79, v216, v79, vcc
